# pad so that the attention and GEMM loops keep their baseline byte offsets
# speedup vs baseline: 1.0070x; 1.0070x over previous
.LBB0_332:
	s_or_b64 exec, exec, s[6:7]
	s_waitcnt lgkmcnt(0)
	s_lshl_b64 s[4:5], s[14:15], 11
	v_ashrrev_i32_e32 v64, 5, v177
	v_lshl_add_u32 v67, v64, 4, v179
	ds_read2_b32 v[70:71], v67 offset1:1
	ds_read2_b32 v[72:73], v67 offset0:2 offset1:3
	ds_read2_b32 v[74:75], v67 offset0:8 offset1:9
	ds_read2_b32 v[76:77], v67 offset0:10 offset1:11
	ds_read2_b32 v[78:79], v67 offset0:16 offset1:17
	ds_read2_b32 v[80:81], v67 offset0:18 offset1:19
	ds_read2_b32 v[82:83], v67 offset0:24 offset1:25
	ds_read2_b32 v[84:85], v67 offset0:26 offset1:27
	s_add_u32 s4, s10, s4
	s_addc_u32 s5, s11, s5
	s_add_u32 s4, s4, s18
	s_addc_u32 s5, s5, s19
	s_add_i32 s31, s31, 1
	v_readlane_b32 s6, v254, 41
	v_readlane_b32 s7, v254, 42
	v_and_b32_e32 v65, 31, v177
	v_lshlrev_b32_e32 v66, 8, v178
	v_lshl_add_u32 v66, v64, 10, v66
	v_lshl_add_u32 v66, v65, 1, v66
	v_add_u32_e32 v66, 0x11000, v66
	s_waitcnt lgkmcnt(0)
	v_rcp_f32_e32 v70, v70
	v_rcp_f32_e32 v71, v71
	v_rcp_f32_e32 v72, v72
	v_rcp_f32_e32 v73, v73
	v_rcp_f32_e32 v74, v74
	v_rcp_f32_e32 v75, v75
	v_rcp_f32_e32 v76, v76
	v_rcp_f32_e32 v77, v77
	v_rcp_f32_e32 v78, v78
	v_rcp_f32_e32 v79, v79
	v_rcp_f32_e32 v80, v80
	v_rcp_f32_e32 v81, v81
	v_rcp_f32_e32 v82, v82
	v_rcp_f32_e32 v83, v83
	v_rcp_f32_e32 v84, v84
	v_rcp_f32_e32 v85, v85
	s_nop 1
	v_mul_f32_e32 v0, v0, v70
	v_cvt_pk_bf16_f32 v0, v0, v193
	ds_write_b16 v66, v0 offset:0
	v_mul_f32_e32 v48, v48, v70
	v_cvt_pk_bf16_f32 v48, v48, v193
	ds_write_b16 v66, v48 offset:64
	v_mul_f32_e32 v32, v32, v70
	v_cvt_pk_bf16_f32 v32, v32, v193
	ds_write_b16 v66, v32 offset:128
	v_mul_f32_e32 v16, v16, v70
	v_cvt_pk_bf16_f32 v16, v16, v193
	ds_write_b16 v66, v16 offset:192
	v_mul_f32_e32 v1, v1, v71
	v_cvt_pk_bf16_f32 v1, v1, v193
	ds_write_b16 v66, v1 offset:256
	v_mul_f32_e32 v49, v49, v71
	v_cvt_pk_bf16_f32 v49, v49, v193
	ds_write_b16 v66, v49 offset:320
	v_mul_f32_e32 v33, v33, v71
	v_cvt_pk_bf16_f32 v33, v33, v193
	ds_write_b16 v66, v33 offset:384
	v_mul_f32_e32 v17, v17, v71
	v_cvt_pk_bf16_f32 v17, v17, v193
	ds_write_b16 v66, v17 offset:448
	s_waitcnt lgkmcnt(7)
	v_mul_f32_e32 v2, v2, v72
	v_cvt_pk_bf16_f32 v2, v2, v193
	ds_write_b16 v66, v2 offset:512
	v_mul_f32_e32 v50, v50, v72
	v_cvt_pk_bf16_f32 v50, v50, v193
	ds_write_b16 v66, v50 offset:576
	v_mul_f32_e32 v34, v34, v72
	v_cvt_pk_bf16_f32 v34, v34, v193
	ds_write_b16 v66, v34 offset:640
	v_mul_f32_e32 v18, v18, v72
	v_cvt_pk_bf16_f32 v18, v18, v193
	ds_write_b16 v66, v18 offset:704
	v_mul_f32_e32 v3, v3, v73
	v_cvt_pk_bf16_f32 v3, v3, v193
	ds_write_b16 v66, v3 offset:768
	v_mul_f32_e32 v51, v51, v73
	v_cvt_pk_bf16_f32 v51, v51, v193
	ds_write_b16 v66, v51 offset:832
	v_mul_f32_e32 v35, v35, v73
	v_cvt_pk_bf16_f32 v35, v35, v193
	ds_write_b16 v66, v35 offset:896
	v_mul_f32_e32 v19, v19, v73
	v_cvt_pk_bf16_f32 v19, v19, v193
	ds_write_b16 v66, v19 offset:960
	s_waitcnt lgkmcnt(7)
	v_mul_f32_e32 v4, v4, v74
	v_cvt_pk_bf16_f32 v4, v4, v193
	ds_write_b16 v66, v4 offset:2048
	v_mul_f32_e32 v52, v52, v74
	v_cvt_pk_bf16_f32 v52, v52, v193
	ds_write_b16 v66, v52 offset:2112
	v_mul_f32_e32 v36, v36, v74
	v_cvt_pk_bf16_f32 v36, v36, v193
	ds_write_b16 v66, v36 offset:2176
	v_mul_f32_e32 v20, v20, v74
	v_cvt_pk_bf16_f32 v20, v20, v193
	ds_write_b16 v66, v20 offset:2240
	v_mul_f32_e32 v5, v5, v75
	v_cvt_pk_bf16_f32 v5, v5, v193
	ds_write_b16 v66, v5 offset:2304
	v_mul_f32_e32 v53, v53, v75
	v_cvt_pk_bf16_f32 v53, v53, v193
	ds_write_b16 v66, v53 offset:2368
	v_mul_f32_e32 v37, v37, v75
	v_cvt_pk_bf16_f32 v37, v37, v193
	ds_write_b16 v66, v37 offset:2432
	v_mul_f32_e32 v21, v21, v75
	v_cvt_pk_bf16_f32 v21, v21, v193
	ds_write_b16 v66, v21 offset:2496
	s_waitcnt lgkmcnt(7)
	v_mul_f32_e32 v6, v6, v76
	v_cvt_pk_bf16_f32 v6, v6, v193
	ds_write_b16 v66, v6 offset:2560
	v_mul_f32_e32 v54, v54, v76
	v_cvt_pk_bf16_f32 v54, v54, v193
	ds_write_b16 v66, v54 offset:2624
	v_mul_f32_e32 v38, v38, v76
	v_cvt_pk_bf16_f32 v38, v38, v193
	ds_write_b16 v66, v38 offset:2688
	v_mul_f32_e32 v22, v22, v76
	v_cvt_pk_bf16_f32 v22, v22, v193
	ds_write_b16 v66, v22 offset:2752
	v_mul_f32_e32 v7, v7, v77
	v_cvt_pk_bf16_f32 v7, v7, v193
	ds_write_b16 v66, v7 offset:2816
	v_mul_f32_e32 v55, v55, v77
	v_cvt_pk_bf16_f32 v55, v55, v193
	ds_write_b16 v66, v55 offset:2880
	v_mul_f32_e32 v39, v39, v77
	v_cvt_pk_bf16_f32 v39, v39, v193
	ds_write_b16 v66, v39 offset:2944
	v_mul_f32_e32 v23, v23, v77
	v_cvt_pk_bf16_f32 v23, v23, v193
	ds_write_b16 v66, v23 offset:3008
	s_waitcnt lgkmcnt(7)
	v_mul_f32_e32 v8, v8, v78
	v_cvt_pk_bf16_f32 v8, v8, v193
	ds_write_b16 v66, v8 offset:4096
	v_mul_f32_e32 v56, v56, v78
	v_cvt_pk_bf16_f32 v56, v56, v193
	ds_write_b16 v66, v56 offset:4160
	v_mul_f32_e32 v40, v40, v78
	v_cvt_pk_bf16_f32 v40, v40, v193
	ds_write_b16 v66, v40 offset:4224
	v_mul_f32_e32 v24, v24, v78
	v_cvt_pk_bf16_f32 v24, v24, v193
	ds_write_b16 v66, v24 offset:4288
	v_mul_f32_e32 v9, v9, v79
	v_cvt_pk_bf16_f32 v9, v9, v193
	ds_write_b16 v66, v9 offset:4352
	v_mul_f32_e32 v57, v57, v79
	v_cvt_pk_bf16_f32 v57, v57, v193
	ds_write_b16 v66, v57 offset:4416
	v_mul_f32_e32 v41, v41, v79
	v_cvt_pk_bf16_f32 v41, v41, v193
	ds_write_b16 v66, v41 offset:4480
	v_mul_f32_e32 v25, v25, v79
	v_cvt_pk_bf16_f32 v25, v25, v193
	ds_write_b16 v66, v25 offset:4544
	s_waitcnt lgkmcnt(7)
	v_mul_f32_e32 v10, v10, v80
	v_cvt_pk_bf16_f32 v10, v10, v193
	ds_write_b16 v66, v10 offset:4608
	v_mul_f32_e32 v58, v58, v80
	v_cvt_pk_bf16_f32 v58, v58, v193
	ds_write_b16 v66, v58 offset:4672
	v_mul_f32_e32 v42, v42, v80
	v_cvt_pk_bf16_f32 v42, v42, v193
	ds_write_b16 v66, v42 offset:4736
	v_mul_f32_e32 v26, v26, v80
	v_cvt_pk_bf16_f32 v26, v26, v193
	ds_write_b16 v66, v26 offset:4800
	v_mul_f32_e32 v11, v11, v81
	v_cvt_pk_bf16_f32 v11, v11, v193
	ds_write_b16 v66, v11 offset:4864
	v_mul_f32_e32 v59, v59, v81
	v_cvt_pk_bf16_f32 v59, v59, v193
	ds_write_b16 v66, v59 offset:4928
	v_mul_f32_e32 v43, v43, v81
	v_cvt_pk_bf16_f32 v43, v43, v193
	ds_write_b16 v66, v43 offset:4992
	v_mul_f32_e32 v27, v27, v81
	v_cvt_pk_bf16_f32 v27, v27, v193
	ds_write_b16 v66, v27 offset:5056
	s_waitcnt lgkmcnt(7)
	v_mul_f32_e32 v12, v12, v82
	v_cvt_pk_bf16_f32 v12, v12, v193
	ds_write_b16 v66, v12 offset:6144
	v_mul_f32_e32 v60, v60, v82
	v_cvt_pk_bf16_f32 v60, v60, v193
	ds_write_b16 v66, v60 offset:6208
	v_mul_f32_e32 v44, v44, v82
	v_cvt_pk_bf16_f32 v44, v44, v193
	ds_write_b16 v66, v44 offset:6272
	v_mul_f32_e32 v28, v28, v82
	v_cvt_pk_bf16_f32 v28, v28, v193
	ds_write_b16 v66, v28 offset:6336
	v_mul_f32_e32 v13, v13, v83
	v_cvt_pk_bf16_f32 v13, v13, v193
	ds_write_b16 v66, v13 offset:6400
	v_mul_f32_e32 v61, v61, v83
	v_cvt_pk_bf16_f32 v61, v61, v193
	ds_write_b16 v66, v61 offset:6464
	v_mul_f32_e32 v45, v45, v83
	v_cvt_pk_bf16_f32 v45, v45, v193
	ds_write_b16 v66, v45 offset:6528
	v_mul_f32_e32 v29, v29, v83
	v_cvt_pk_bf16_f32 v29, v29, v193
	ds_write_b16 v66, v29 offset:6592
	s_waitcnt lgkmcnt(7)
	v_mul_f32_e32 v14, v14, v84
	v_cvt_pk_bf16_f32 v14, v14, v193
	ds_write_b16 v66, v14 offset:6656
	v_mul_f32_e32 v62, v62, v84
	v_cvt_pk_bf16_f32 v62, v62, v193
	ds_write_b16 v66, v62 offset:6720
	v_mul_f32_e32 v46, v46, v84
	v_cvt_pk_bf16_f32 v46, v46, v193
	ds_write_b16 v66, v46 offset:6784
	v_mul_f32_e32 v30, v30, v84
	v_cvt_pk_bf16_f32 v30, v30, v193
	ds_write_b16 v66, v30 offset:6848
	v_mul_f32_e32 v15, v15, v85
	v_cvt_pk_bf16_f32 v15, v15, v193
	ds_write_b16 v66, v15 offset:6912
	v_mul_f32_e32 v63, v63, v85
	v_cvt_pk_bf16_f32 v63, v63, v193
	ds_write_b16 v66, v63 offset:6976
	v_mul_f32_e32 v47, v47, v85
	v_cvt_pk_bf16_f32 v47, v47, v193
	ds_write_b16 v66, v47 offset:7040
	v_mul_f32_e32 v31, v31, v85
	v_cvt_pk_bf16_f32 v31, v31, v193
	ds_write_b16 v66, v31 offset:7104
	v_lshrrev_b32_e32 v64, 4, v177
	v_and_b32_e32 v65, 15, v177
	v_lshlrev_b32_e32 v66, 8, v178
	v_lshl_add_u32 v66, v64, 8, v66
	v_lshl_add_u32 v66, v65, 4, v66
	v_add_u32_e32 v66, 0x11000, v66
	v_add_u32_e32 v68, v178, v64
	v_mov_b32_e32 v69, 0
	v_lshlrev_b64 v[68:69], 11, v[68:69]
	v_lshl_add_u64 v[68:69], s[4:5], 0, v[68:69]
	v_lshlrev_b32_e32 v70, 4, v65
	v_mov_b32_e32 v71, 0
	v_lshl_add_u64 v[68:69], v[68:69], 0, v[70:71]
	s_waitcnt lgkmcnt(0)
	ds_read_b128 v[0:3], v66 offset:0
	ds_read_b128 v[4:7], v66 offset:1024
	ds_read_b128 v[8:11], v66 offset:2048
	ds_read_b128 v[12:15], v66 offset:3072
	ds_read_b128 v[16:19], v66 offset:4096
	ds_read_b128 v[20:23], v66 offset:5120
	ds_read_b128 v[24:27], v66 offset:6144
	ds_read_b128 v[28:31], v66 offset:7168
	s_waitcnt lgkmcnt(7)
	global_store_dwordx4 v[68:69], v[0:3], off offset:1024
	v_add_co_u32_e32 v68, vcc, 0x2000, v68
	s_nop 1
	v_addc_co_u32_e32 v69, vcc, 0, v69, vcc
	s_waitcnt lgkmcnt(6)
	global_store_dwordx4 v[68:69], v[4:7], off offset:1024
	v_add_co_u32_e32 v68, vcc, 0x2000, v68
	s_nop 1
	v_addc_co_u32_e32 v69, vcc, 0, v69, vcc
	s_waitcnt lgkmcnt(5)
	global_store_dwordx4 v[68:69], v[8:11], off offset:1024
	v_add_co_u32_e32 v68, vcc, 0x2000, v68
	s_nop 1
	v_addc_co_u32_e32 v69, vcc, 0, v69, vcc
	s_waitcnt lgkmcnt(4)
	global_store_dwordx4 v[68:69], v[12:15], off offset:1024
	v_add_co_u32_e32 v68, vcc, 0x2000, v68
	s_nop 1
	v_addc_co_u32_e32 v69, vcc, 0, v69, vcc
	s_waitcnt lgkmcnt(3)
	global_store_dwordx4 v[68:69], v[16:19], off offset:1024
	v_add_co_u32_e32 v68, vcc, 0x2000, v68
	s_nop 1
	v_addc_co_u32_e32 v69, vcc, 0, v69, vcc
	s_waitcnt lgkmcnt(2)
	global_store_dwordx4 v[68:69], v[20:23], off offset:1024
	v_add_co_u32_e32 v68, vcc, 0x2000, v68
	s_nop 1
	v_addc_co_u32_e32 v69, vcc, 0, v69, vcc
	s_waitcnt lgkmcnt(1)
	global_store_dwordx4 v[68:69], v[24:27], off offset:1024
	v_add_co_u32_e32 v68, vcc, 0x2000, v68
	s_nop 1
	v_addc_co_u32_e32 v69, vcc, 0, v69, vcc
	s_waitcnt lgkmcnt(0)
	global_store_dwordx4 v[68:69], v[28:31], off offset:1024
	s_branch .Lattn_epi_pad_end
	s_nop 0
	s_nop 0
	s_nop 0
	s_nop 0
	s_nop 0
	s_nop 0
	s_nop 0
	s_nop 0
	s_nop 0
	s_nop 0
	s_nop 0
	s_nop 0
	s_nop 0
	s_nop 0
	s_nop 0
	s_nop 0
	s_nop 0
	s_nop 0
	s_nop 0
	s_nop 0
	s_nop 0
	s_nop 0
	s_nop 0
	s_nop 0
	s_nop 0
	s_nop 0
	s_nop 0
	s_nop 0
	s_nop 0
	s_nop 0
	s_nop 0
	s_nop 0
	s_nop 0
	s_nop 0
	s_nop 0
	s_nop 0
	s_nop 0
	s_nop 0
	s_nop 0
	s_nop 0
	s_nop 0
	s_nop 0
	s_nop 0
	s_nop 0
	s_nop 0
	s_nop 0
	s_nop 0
	s_nop 0
	s_nop 0
	s_nop 0
	s_nop 0
	s_nop 0
	s_nop 0
	s_nop 0
	s_nop 0
	s_nop 0
	s_nop 0
	s_nop 0
	s_nop 0
	s_nop 0
	s_nop 0
	s_nop 0
	s_nop 0
	s_nop 0
	s_nop 0
	s_nop 0
	s_nop 0
	s_nop 0
	s_nop 0
	s_nop 0
	s_nop 0
	s_nop 0
	s_nop 0
	s_nop 0
	s_nop 0
	s_nop 0
	s_nop 0
	s_nop 0
	s_nop 0
	s_nop 0
	s_nop 0
	s_nop 0
	s_nop 0
	s_nop 0
	s_nop 0
	s_nop 0
	s_nop 0
	s_nop 0
	s_nop 0
	s_nop 0
	s_nop 0
	s_nop 0
	s_nop 0
	s_nop 0
	s_nop 0
	s_nop 0
	s_nop 0
	s_nop 0
	s_nop 0
	s_nop 0
	s_nop 0
	s_nop 0
	s_nop 0
	s_nop 0
	s_nop 0
	s_nop 0
	s_nop 0
.Lattn_epi_pad_end:
	s_mul_i32 s4, s31, s82
	s_add_i32 s14, s4, s6
	s_cmpk_lt_i32 s14, 0x480
	s_cbranch_scc0 .LBB0_358
